# in-proj krope tile (64 real + 192 zero-padded weight rows): MFMA blocks whose weight fragments are all zero are branched over (accumulators stay at their zero init)
# speedup vs baseline: 1.0053x; 1.0032x over previous
.LBB0_1515:
	s_and_b32 s18, s6, 3
	s_lshl_b32 s12, s8, 6
	v_and_b32_e32 v19, 48, v18
	s_lshl_b32 s6, s8, 13
	v_lshlrev_b32_e32 v20, 6, v18
	s_movk_i32 s8, 0x3c0
	v_lshlrev_b32_e32 v18, 2, v18
	s_add_i32 s45, s78, 0x18000
	v_and_or_b32 v19, v20, s8, v19
	v_and_b32_e32 v18, 32, v18
	s_add_i32 s24, s45, s7
	v_bitop3_b32 v20, v19, s6, v18 bitop3:0xde
	s_lshl_b32 s6, s18, 12
	v_lshl_add_u64 v[10:11], v[10:11], 0, s[64:65]
	s_mov_b32 m0, s24
	s_add_i32 s25, s24, 0x2000
	s_add_i32 s26, s16, 0x8000
	s_add_i32 s27, s16, 0xa000
	s_waitcnt vmcnt(2)
	s_barrier
	global_load_lds_dwordx4 v[10:11], off
	v_lshl_add_u64 v[8:9], v[8:9], 0, s[64:65]
	s_mov_b32 m0, s25
	s_add_u32 s8, s2, 0x80080
	global_load_lds_dwordx4 v[8:9], off
	v_lshl_add_u64 v[6:7], v[6:7], 0, s[64:65]
	s_mov_b32 m0, s26
	s_addc_u32 s9, s3, 0
	s_add_i32 s74, s78, 0x1c000
	global_load_lds_dwordx4 v[6:7], off
	v_lshl_add_u64 v[4:5], v[4:5], 0, s[64:65]
	s_mov_b32 m0, s27
	s_add_i32 s34, s74, s7
	global_load_lds_dwordx4 v[4:5], off
	v_lshl_add_u64 v[4:5], s[8:9], 0, v[2:3]
	s_mov_b32 m0, s34
	s_add_i32 s35, s34, 0x2000
	global_load_lds_dwordx4 v[4:5], off
	v_lshl_add_u64 v[4:5], s[8:9], 0, v[136:137]
	s_mov_b32 m0, s35
	v_bitop3_b32 v142, v19, s6, v18 bitop3:0xde
	global_load_lds_dwordx4 v[4:5], off
	v_readlane_b32 s6, v254, 32
	v_lshlrev_b32_e32 v4, 15, v12
	v_readlane_b32 s7, v254, 33
	s_add_u32 s37, s38, s6
	v_and_b32_e32 v4, 0xffff0000, v4
	s_addc_u32 s40, s39, s7
	v_readlane_b32 s6, v254, 31
	v_lshl_add_u32 v4, v13, 12, v4
	v_and_b32_e32 v5, 1, v12
	s_add_u32 s6, s38, s6
	v_readlane_b32 s7, v254, 34
	v_lshl_or_b32 v4, v5, 6, v4
	s_addc_u32 s7, s39, s7
	v_lshl_add_u32 v4, v14, 1, v4
	v_mov_b32_e32 v5, v3
	v_lshl_add_u64 v[138:139], s[6:7], 0, v[4:5]
	v_lshlrev_b32_e32 v4, 15, v15
	v_and_b32_e32 v4, 0xffff0000, v4
	v_lshl_add_u32 v4, v16, 12, v4
	v_and_b32_e32 v5, 1, v15
	v_lshl_or_b32 v4, v5, 6, v4
	v_lshl_add_u32 v4, v17, 1, v4
	v_mov_b32_e32 v5, v3
	s_waitcnt vmcnt(6)
	v_lshl_add_u64 v[140:141], s[6:7], 0, v[4:5]
	v_readlane_b32 s6, v254, 37
	s_add_u32 s41, s38, s6
	v_readlane_b32 s6, v254, 56
	v_mov_b32_e32 v4, 0
	v_readlane_b32 s50, v253, 16
	s_mov_b32 s67, s36
	s_addc_u32 s42, s39, s6
	s_mov_b32 s43, -2
	s_mov_b64 s[6:7], 0
	v_add_u32_e32 v143, s78, v20
	v_mov_b32_e32 v5, v4
	v_mov_b32_e32 v6, v4
	v_mov_b32_e32 v7, v4
	v_mov_b32_e32 v8, v4
	v_mov_b32_e32 v9, v4
	v_mov_b32_e32 v10, v4
	v_mov_b32_e32 v11, v4
	v_mov_b32_e32 v20, v4
	v_mov_b32_e32 v21, v4
	v_mov_b32_e32 v22, v4
	v_mov_b32_e32 v23, v4
	v_mov_b32_e32 v24, v4
	v_mov_b32_e32 v25, v4
	v_mov_b32_e32 v26, v4
	v_mov_b32_e32 v27, v4
	v_mov_b32_e32 v36, v4
	v_mov_b32_e32 v37, v4
	v_mov_b32_e32 v38, v4
	v_mov_b32_e32 v39, v4
	v_mov_b32_e32 v40, v4
	v_mov_b32_e32 v41, v4
	v_mov_b32_e32 v42, v4
	v_mov_b32_e32 v43, v4
	v_mov_b32_e32 v52, v4
	v_mov_b32_e32 v53, v4
	v_mov_b32_e32 v54, v4
	v_mov_b32_e32 v55, v4
	v_mov_b32_e32 v56, v4
	v_mov_b32_e32 v57, v4
	v_mov_b32_e32 v58, v4
	v_mov_b32_e32 v59, v4
	v_mov_b32_e32 v12, v4
	v_mov_b32_e32 v13, v4
	v_mov_b32_e32 v14, v4
	v_mov_b32_e32 v15, v4
	v_mov_b32_e32 v16, v4
	v_mov_b32_e32 v17, v4
	v_mov_b32_e32 v18, v4
	v_mov_b32_e32 v19, v4
	v_mov_b32_e32 v28, v4
	v_mov_b32_e32 v29, v4
	v_mov_b32_e32 v30, v4
	v_mov_b32_e32 v31, v4
	v_mov_b32_e32 v32, v4
	v_mov_b32_e32 v33, v4
	v_mov_b32_e32 v34, v4
	v_mov_b32_e32 v35, v4
	v_mov_b32_e32 v44, v4
	v_mov_b32_e32 v45, v4
	v_mov_b32_e32 v46, v4
	v_mov_b32_e32 v47, v4
	v_mov_b32_e32 v48, v4
	v_mov_b32_e32 v49, v4
	v_mov_b32_e32 v50, v4
	v_mov_b32_e32 v51, v4
	v_mov_b32_e32 v60, v4
	v_mov_b32_e32 v61, v4
	v_mov_b32_e32 v62, v4
	v_mov_b32_e32 v63, v4
	v_mov_b32_e32 v64, v4
	v_mov_b32_e32 v65, v4
	v_mov_b32_e32 v66, v4
	v_mov_b32_e32 v67, v4
	v_mov_b32_e32 v68, v4
	v_mov_b32_e32 v69, v4
	v_mov_b32_e32 v70, v4
	v_mov_b32_e32 v71, v4
	v_mov_b32_e32 v72, v4
	v_mov_b32_e32 v73, v4
	v_mov_b32_e32 v74, v4
	v_mov_b32_e32 v75, v4
	v_mov_b32_e32 v84, v4
	v_mov_b32_e32 v85, v4
	v_mov_b32_e32 v86, v4
	v_mov_b32_e32 v87, v4
	v_mov_b32_e32 v88, v4
	v_mov_b32_e32 v89, v4
	v_mov_b32_e32 v90, v4
	v_mov_b32_e32 v91, v4
	v_mov_b32_e32 v100, v4
	v_mov_b32_e32 v101, v4
	v_mov_b32_e32 v102, v4
	v_mov_b32_e32 v103, v4
	v_mov_b32_e32 v104, v4
	v_mov_b32_e32 v105, v4
	v_mov_b32_e32 v106, v4
	v_mov_b32_e32 v107, v4
	v_mov_b32_e32 v116, v4
	v_mov_b32_e32 v117, v4
	v_mov_b32_e32 v118, v4
	v_mov_b32_e32 v119, v4
	v_mov_b32_e32 v120, v4
	v_mov_b32_e32 v121, v4
	v_mov_b32_e32 v122, v4
	v_mov_b32_e32 v123, v4
	v_mov_b32_e32 v76, v4
	v_mov_b32_e32 v77, v4
	v_mov_b32_e32 v78, v4
	v_mov_b32_e32 v79, v4
	v_mov_b32_e32 v80, v4
	v_mov_b32_e32 v81, v4
	v_mov_b32_e32 v82, v4
	v_mov_b32_e32 v83, v4
	v_mov_b32_e32 v92, v4
	v_mov_b32_e32 v93, v4
	v_mov_b32_e32 v94, v4
	v_mov_b32_e32 v95, v4
	v_mov_b32_e32 v96, v4
	v_mov_b32_e32 v97, v4
	v_mov_b32_e32 v98, v4
	v_mov_b32_e32 v99, v4
	v_mov_b32_e32 v108, v4
	v_mov_b32_e32 v109, v4
	v_mov_b32_e32 v110, v4
	v_mov_b32_e32 v111, v4
	v_mov_b32_e32 v112, v4
	v_mov_b32_e32 v113, v4
	v_mov_b32_e32 v114, v4
	v_mov_b32_e32 v115, v4
	v_mov_b32_e32 v124, v4
	v_mov_b32_e32 v125, v4
	v_mov_b32_e32 v126, v4
	v_mov_b32_e32 v127, v4
	v_mov_b32_e32 v128, v4
	v_mov_b32_e32 v129, v4
	v_mov_b32_e32 v130, v4
	v_mov_b32_e32 v131, v4
	v_readlane_b32 s58, v253, 62
	v_readlane_b32 s48, v254, 57
	v_readlane_b32 s51, v253, 17
	v_readlane_b32 s73, v254, 13
	s_mov_b32 s49, 0x38400000
	s_barrier
	v_readlane_b32 s59, v253, 63
	s_nop 0
	s_cmp_eq_u32 s48, 13
	s_cselect_b32 s100, 1, 0
	s_bfe_u32 s101, s21, 0x20006
	s_cmp_gt_u32 s101, 1
	s_cselect_b32 s101, s100, 0
.LBB0_1516:
	v_add_u32_e32 v156, s83, v142
	v_add_u32_e32 v172, s44, v142
	s_add_u32 s8, s37, s6
	ds_read_b128 v[144:147], v156
	ds_read_b128 v[148:151], v156 offset:1024
	ds_read_b128 v[152:155], v156 offset:2048
	ds_read_b128 v[156:159], v156 offset:3072
	ds_read_b128 v[160:163], v172
	ds_read_b128 v[164:167], v172 offset:1024
	ds_read_b128 v[168:171], v172 offset:2048
	ds_read_b128 v[172:175], v172 offset:3072
	s_addc_u32 s9, s40, s7
	s_add_u32 s8, s8, 0x20400100
	s_addc_u32 s9, s9, 0
	s_add_u32 s46, s41, s6
	s_addc_u32 s47, s42, s7
	s_cmpk_eq_i32 s6, 0xf00
	s_cselect_b32 s11, s5, s9
	s_cselect_b32 s10, s4, s8
	s_cselect_b32 s9, s3, s47
	s_cselect_b32 s8, s2, s46
	v_lshl_add_u64 v[208:209], v[138:139], 0, s[6:7]
	s_add_i32 m0, s16, 0xc000
	ds_read_b128 v[176:179], v143
	ds_read_b128 v[180:183], v143 offset:1024
	ds_read_b128 v[184:187], v143 offset:2048
	ds_read_b128 v[188:191], v143 offset:3072
	ds_read_b128 v[192:195], v143 offset:4096
	ds_read_b128 v[196:199], v143 offset:5120
	ds_read_b128 v[200:203], v143 offset:6144
	ds_read_b128 v[204:207], v143 offset:7168
	global_load_lds_dwordx4 v[208:209], off
	v_lshl_add_u64 v[208:209], v[140:141], 0, s[6:7]
	s_add_i32 m0, s16, 0xe000
	s_nop 0
	global_load_lds_dwordx4 v[208:209], off
	s_waitcnt vmcnt(8)
	s_waitcnt lgkmcnt(0)
	s_barrier
	s_setprio 1
	s_waitcnt lgkmcnt(0)
	s_cmp_lg_u32 s101, 0
	s_cbranch_scc1 .Lt13a_0
	v_mfma_f32_16x16x32_bf16 v[128:131], v[144:147], v[176:179], v[128:131]
	v_mfma_f32_16x16x32_bf16 v[128:131], v[148:151], v[180:183], v[128:131]
	v_mfma_f32_16x16x32_bf16 v[112:115], v[144:147], v[184:187], v[112:115]
	v_mfma_f32_16x16x32_bf16 v[112:115], v[148:151], v[188:191], v[112:115]
	v_mfma_f32_16x16x32_bf16 v[96:99], v[144:147], v[192:195], v[96:99]
	v_mfma_f32_16x16x32_bf16 v[96:99], v[148:151], v[196:199], v[96:99]
	v_mfma_f32_16x16x32_bf16 v[80:83], v[144:147], v[200:203], v[80:83]
	v_mfma_f32_16x16x32_bf16 v[80:83], v[148:151], v[204:207], v[80:83]
	v_mfma_f32_16x16x32_bf16 v[76:79], v[152:155], v[200:203], v[76:79]
	v_mfma_f32_16x16x32_bf16 v[76:79], v[156:159], v[204:207], v[76:79]
	v_mfma_f32_16x16x32_bf16 v[92:95], v[152:155], v[192:195], v[92:95]
	v_mfma_f32_16x16x32_bf16 v[92:95], v[156:159], v[196:199], v[92:95]
	v_mfma_f32_16x16x32_bf16 v[108:111], v[152:155], v[184:187], v[108:111]
	v_mfma_f32_16x16x32_bf16 v[108:111], v[156:159], v[188:191], v[108:111]
	v_mfma_f32_16x16x32_bf16 v[124:127], v[152:155], v[176:179], v[124:127]
	v_mfma_f32_16x16x32_bf16 v[124:127], v[156:159], v[180:183], v[124:127]
.Lt13a_0:
	s_setprio 0
	s_setprio 1
	s_cmp_lg_u32 s100, 0
	s_cbranch_scc1 .Lt13b_0
	v_mfma_f32_16x16x32_bf16 v[120:123], v[160:163], v[176:179], v[120:123]
	v_mfma_f32_16x16x32_bf16 v[120:123], v[164:167], v[180:183], v[120:123]
	v_mfma_f32_16x16x32_bf16 v[104:107], v[160:163], v[184:187], v[104:107]
	v_mfma_f32_16x16x32_bf16 v[104:107], v[164:167], v[188:191], v[104:107]
	v_mfma_f32_16x16x32_bf16 v[88:91], v[160:163], v[192:195], v[88:91]
	v_mfma_f32_16x16x32_bf16 v[88:91], v[164:167], v[196:199], v[88:91]
	v_mfma_f32_16x16x32_bf16 v[72:75], v[160:163], v[200:203], v[72:75]
	v_mfma_f32_16x16x32_bf16 v[72:75], v[164:167], v[204:207], v[72:75]
	v_mfma_f32_16x16x32_bf16 v[68:71], v[168:171], v[200:203], v[68:71]
	v_mfma_f32_16x16x32_bf16 v[68:71], v[172:175], v[204:207], v[68:71]
	v_mfma_f32_16x16x32_bf16 v[84:87], v[168:171], v[192:195], v[84:87]
	v_mfma_f32_16x16x32_bf16 v[84:87], v[172:175], v[196:199], v[84:87]
	v_mfma_f32_16x16x32_bf16 v[100:103], v[168:171], v[184:187], v[100:103]
	v_mfma_f32_16x16x32_bf16 v[100:103], v[172:175], v[188:191], v[100:103]
	v_mfma_f32_16x16x32_bf16 v[116:119], v[168:171], v[176:179], v[116:119]
	v_mfma_f32_16x16x32_bf16 v[116:119], v[172:175], v[180:183], v[116:119]
.Lt13b_0:
	s_setprio 0
	s_barrier
	s_mov_b32 m0, s13
	v_lshl_add_u64 v[208:209], s[8:9], 0, v[2:3]
	s_add_u32 s46, s8, 0x80000
	ds_read_b128 v[176:179], v143 offset:16384
	ds_read_b128 v[180:183], v143 offset:17408
	ds_read_b128 v[184:187], v143 offset:18432
	ds_read_b128 v[188:191], v143 offset:19456
	ds_read_b128 v[192:195], v143 offset:20480
	ds_read_b128 v[196:199], v143 offset:21504
	ds_read_b128 v[200:203], v143 offset:22528
	ds_read_b128 v[204:207], v143 offset:23552
	global_load_lds_dwordx4 v[208:209], off
	v_lshl_add_u64 v[210:211], s[8:9], 0, v[136:137]
	s_mov_b32 m0, s14
	s_addc_u32 s47, s9, 0
	global_load_lds_dwordx4 v[210:211], off
	v_lshl_add_u64 v[216:217], s[46:47], 0, v[2:3]
	s_mov_b32 m0, s15
	v_lshl_add_u64 v[218:219], s[10:11], 0, v[134:135]
	global_load_lds_dwordx4 v[216:217], off
	v_lshl_add_u64 v[216:217], s[46:47], 0, v[136:137]
	s_mov_b32 m0, s19
	s_nop 0
	global_load_lds_dwordx4 v[216:217], off
	v_lshl_add_u64 v[216:217], s[10:11], 0, v[132:133]
	s_mov_b32 m0, s16
	s_nop 0
	global_load_lds_dwordx4 v[216:217], off
	s_mov_b32 m0, s20
	s_nop 0
	global_load_lds_dwordx4 v[218:219], off
	s_waitcnt vmcnt(8)
	s_waitcnt lgkmcnt(0)
	s_barrier
	s_setprio 1
	s_waitcnt lgkmcnt(0)
	s_cmp_lg_u32 s101, 0
	s_cbranch_scc1 .Lt13a_1
	v_mfma_f32_16x16x32_bf16 v[64:67], v[144:147], v[176:179], v[64:67]
	v_mfma_f32_16x16x32_bf16 v[64:67], v[148:151], v[180:183], v[64:67]
	v_mfma_f32_16x16x32_bf16 v[48:51], v[144:147], v[184:187], v[48:51]
	v_mfma_f32_16x16x32_bf16 v[48:51], v[148:151], v[188:191], v[48:51]
	v_mfma_f32_16x16x32_bf16 v[32:35], v[144:147], v[192:195], v[32:35]
	v_mfma_f32_16x16x32_bf16 v[32:35], v[148:151], v[196:199], v[32:35]
	v_mfma_f32_16x16x32_bf16 v[16:19], v[144:147], v[200:203], v[16:19]
	v_mfma_f32_16x16x32_bf16 v[16:19], v[148:151], v[204:207], v[16:19]
	v_mfma_f32_16x16x32_bf16 v[12:15], v[152:155], v[200:203], v[12:15]
	v_mfma_f32_16x16x32_bf16 v[12:15], v[156:159], v[204:207], v[12:15]
	v_mfma_f32_16x16x32_bf16 v[28:31], v[152:155], v[192:195], v[28:31]
	v_mfma_f32_16x16x32_bf16 v[28:31], v[156:159], v[196:199], v[28:31]
	v_mfma_f32_16x16x32_bf16 v[44:47], v[152:155], v[184:187], v[44:47]
	v_mfma_f32_16x16x32_bf16 v[44:47], v[156:159], v[188:191], v[44:47]
	v_mfma_f32_16x16x32_bf16 v[60:63], v[152:155], v[176:179], v[60:63]
	v_mfma_f32_16x16x32_bf16 v[60:63], v[156:159], v[180:183], v[60:63]
.Lt13a_1:
	s_setprio 0
	s_setprio 1
	s_cmp_lg_u32 s100, 0
	s_cbranch_scc1 .Lt13b_1
	v_mfma_f32_16x16x32_bf16 v[56:59], v[160:163], v[176:179], v[56:59]
	v_mfma_f32_16x16x32_bf16 v[56:59], v[164:167], v[180:183], v[56:59]
	v_mfma_f32_16x16x32_bf16 v[40:43], v[160:163], v[184:187], v[40:43]
	v_mfma_f32_16x16x32_bf16 v[40:43], v[164:167], v[188:191], v[40:43]
	v_mfma_f32_16x16x32_bf16 v[24:27], v[160:163], v[192:195], v[24:27]
	v_mfma_f32_16x16x32_bf16 v[24:27], v[164:167], v[196:199], v[24:27]
	v_mfma_f32_16x16x32_bf16 v[8:11], v[160:163], v[200:203], v[8:11]
	v_mfma_f32_16x16x32_bf16 v[8:11], v[164:167], v[204:207], v[8:11]
	v_mfma_f32_16x16x32_bf16 v[4:7], v[168:171], v[200:203], v[4:7]
	v_mfma_f32_16x16x32_bf16 v[4:7], v[172:175], v[204:207], v[4:7]
	v_mfma_f32_16x16x32_bf16 v[20:23], v[168:171], v[192:195], v[20:23]
	v_mfma_f32_16x16x32_bf16 v[20:23], v[172:175], v[196:199], v[20:23]
	v_mfma_f32_16x16x32_bf16 v[36:39], v[168:171], v[184:187], v[36:39]
	v_mfma_f32_16x16x32_bf16 v[36:39], v[172:175], v[188:191], v[36:39]
	v_mfma_f32_16x16x32_bf16 v[52:55], v[168:171], v[176:179], v[52:55]
	v_mfma_f32_16x16x32_bf16 v[52:55], v[172:175], v[180:183], v[52:55]
.Lt13b_1:
	s_setprio 0
	s_barrier
	v_add_u32_e32 v156, s45, v142
	v_add_u32_e32 v172, s74, v142
	ds_read_b128 v[144:147], v156
	ds_read_b128 v[148:151], v156 offset:1024
	ds_read_b128 v[152:155], v156 offset:2048
	ds_read_b128 v[156:159], v156 offset:3072
	ds_read_b128 v[160:163], v172
	ds_read_b128 v[164:167], v172 offset:1024
	ds_read_b128 v[168:171], v172 offset:2048
	ds_read_b128 v[172:175], v172 offset:3072
	s_add_u32 s10, s10, 0x80000
	s_addc_u32 s11, s11, 0
	s_mov_b32 m0, s22
	v_lshl_add_u64 v[220:221], s[10:11], 0, v[132:133]
	ds_read_b128 v[176:179], v143 offset:32768
	ds_read_b128 v[180:183], v143 offset:33792
	ds_read_b128 v[184:187], v143 offset:34816
	ds_read_b128 v[188:191], v143 offset:35840
	ds_read_b128 v[192:195], v143 offset:36864
	ds_read_b128 v[196:199], v143 offset:37888
	ds_read_b128 v[200:203], v143 offset:38912
	ds_read_b128 v[204:207], v143 offset:39936
	global_load_lds_dwordx4 v[220:221], off
	v_lshl_add_u64 v[220:221], s[10:11], 0, v[134:135]
	s_mov_b32 m0, s23
	s_nop 0
	global_load_lds_dwordx4 v[220:221], off
	s_waitcnt vmcnt(8)
	s_waitcnt lgkmcnt(0)
	s_barrier
	s_setprio 1
	s_waitcnt lgkmcnt(0)
	s_cmp_lg_u32 s101, 0
	s_cbranch_scc1 .Lt13a_2
	v_mfma_f32_16x16x32_bf16 v[128:131], v[144:147], v[176:179], v[128:131]
	v_mfma_f32_16x16x32_bf16 v[128:131], v[148:151], v[180:183], v[128:131]
	v_mfma_f32_16x16x32_bf16 v[112:115], v[144:147], v[184:187], v[112:115]
	v_mfma_f32_16x16x32_bf16 v[112:115], v[148:151], v[188:191], v[112:115]
	v_mfma_f32_16x16x32_bf16 v[96:99], v[144:147], v[192:195], v[96:99]
	v_mfma_f32_16x16x32_bf16 v[96:99], v[148:151], v[196:199], v[96:99]
	v_mfma_f32_16x16x32_bf16 v[80:83], v[144:147], v[200:203], v[80:83]
	v_mfma_f32_16x16x32_bf16 v[80:83], v[148:151], v[204:207], v[80:83]
	v_mfma_f32_16x16x32_bf16 v[76:79], v[152:155], v[200:203], v[76:79]
	v_mfma_f32_16x16x32_bf16 v[76:79], v[156:159], v[204:207], v[76:79]
	v_mfma_f32_16x16x32_bf16 v[92:95], v[152:155], v[192:195], v[92:95]
	v_mfma_f32_16x16x32_bf16 v[92:95], v[156:159], v[196:199], v[92:95]
	v_mfma_f32_16x16x32_bf16 v[108:111], v[152:155], v[184:187], v[108:111]
	v_mfma_f32_16x16x32_bf16 v[108:111], v[156:159], v[188:191], v[108:111]
	v_mfma_f32_16x16x32_bf16 v[124:127], v[152:155], v[176:179], v[124:127]
	v_mfma_f32_16x16x32_bf16 v[124:127], v[156:159], v[180:183], v[124:127]

.Lt13b_2:
	s_setprio 0
	s_barrier
	s_mov_b32 m0, s24
	v_lshl_add_u64 v[208:209], v[208:209], 0, s[64:65]
	s_add_u32 s8, s8, 0x80080
	ds_read_b128 v[176:179], v143 offset:49152
	ds_read_b128 v[180:183], v143 offset:50176
	ds_read_b128 v[184:187], v143 offset:51200
	ds_read_b128 v[188:191], v143 offset:52224
	ds_read_b128 v[192:195], v143 offset:53248
	ds_read_b128 v[196:199], v143 offset:54272
	ds_read_b128 v[200:203], v143 offset:55296
	ds_read_b128 v[204:207], v143 offset:56320
	global_load_lds_dwordx4 v[208:209], off
	v_lshl_add_u64 v[208:209], v[210:211], 0, s[64:65]
	s_mov_b32 m0, s25
	s_addc_u32 s9, s9, 0
	global_load_lds_dwordx4 v[208:209], off
	v_lshl_add_u64 v[208:209], s[8:9], 0, v[2:3]
	s_mov_b32 m0, s34
	s_nop 0
	global_load_lds_dwordx4 v[208:209], off
	v_lshl_add_u64 v[208:209], s[8:9], 0, v[136:137]
	s_mov_b32 m0, s35
	s_nop 0
	global_load_lds_dwordx4 v[208:209], off
	v_lshl_add_u64 v[208:209], v[216:217], 0, s[64:65]
	s_mov_b32 m0, s26
	s_nop 0
	global_load_lds_dwordx4 v[208:209], off
	v_lshl_add_u64 v[208:209], v[218:219], 0, s[64:65]
	s_mov_b32 m0, s27
	s_nop 0
	global_load_lds_dwordx4 v[208:209], off
	s_waitcnt vmcnt(8)
	s_waitcnt lgkmcnt(0)
	s_barrier
	s_setprio 1
	s_waitcnt lgkmcnt(0)
	s_cmp_lg_u32 s101, 0
	s_cbranch_scc1 .Lt13a_3
	v_mfma_f32_16x16x32_bf16 v[64:67], v[144:147], v[176:179], v[64:67]
	v_mfma_f32_16x16x32_bf16 v[64:67], v[148:151], v[180:183], v[64:67]
	v_mfma_f32_16x16x32_bf16 v[48:51], v[144:147], v[184:187], v[48:51]
	v_mfma_f32_16x16x32_bf16 v[48:51], v[148:151], v[188:191], v[48:51]
	v_mfma_f32_16x16x32_bf16 v[32:35], v[144:147], v[192:195], v[32:35]
	v_mfma_f32_16x16x32_bf16 v[32:35], v[148:151], v[196:199], v[32:35]
	v_mfma_f32_16x16x32_bf16 v[16:19], v[144:147], v[200:203], v[16:19]
	v_mfma_f32_16x16x32_bf16 v[16:19], v[148:151], v[204:207], v[16:19]
	v_mfma_f32_16x16x32_bf16 v[12:15], v[152:155], v[200:203], v[12:15]
	v_mfma_f32_16x16x32_bf16 v[12:15], v[156:159], v[204:207], v[12:15]
	v_mfma_f32_16x16x32_bf16 v[28:31], v[152:155], v[192:195], v[28:31]
	v_mfma_f32_16x16x32_bf16 v[28:31], v[156:159], v[196:199], v[28:31]
	v_mfma_f32_16x16x32_bf16 v[44:47], v[152:155], v[184:187], v[44:47]
	v_mfma_f32_16x16x32_bf16 v[44:47], v[156:159], v[188:191], v[44:47]
	v_mfma_f32_16x16x32_bf16 v[60:63], v[152:155], v[176:179], v[60:63]
	v_mfma_f32_16x16x32_bf16 v[60:63], v[156:159], v[180:183], v[60:63]

.Lt13b_3:
	s_setprio 0
	s_barrier
	s_add_i32 s43, s43, 2
	s_add_u32 s6, s6, 0x100
	s_addc_u32 s7, s7, 0
	s_cmp_gt_u32 s43, 29
	s_cbranch_scc0 .LBB0_1516
	s_cmpk_lt_u32 s21, 0x100
	s_cbranch_scc0 .LBB0_1519
	s_barrier
